# grid barrier spin loops hand-written with two polls in flight (half the poll period), bounded spin kept
# speedup vs baseline: 1.0036x; 1.0036x over previous
; __device__ __forceinline__ unsigned xb_ld(unsigned* p)              { return __hip_atomic_load(p, __ATOMIC_RELAXED, __HIP_MEMORY_SCOPE_AGENT); }
; __device__ __forceinline__ unsigned xb_add(unsigned* p, unsigned v) { return __hip_atomic_fetch_add(p, v, __ATOMIC_RELAXED, __HIP_MEMORY_SCOPE_AGENT); }
; #define XB_SPIN(cond, bar) do { unsigned _sp = 0; while (cond) { __builtin_amdgcn_s_sleep(1); \
;     if ((++_sp & 255u) == 0u) { if (xb_ld(&(bar)[XB_TMO])) break; if (_sp > XB_SPIN_CAP) { atomicAdd(&(bar)[XB_TMO], 1u); break; } } } } while (0)
; __device__ __forceinline__ void xcd_barrier(const XcdBarrier& b) {
;     ...
;         const unsigned old = xb_add(&bar[XB_XSUB(b.x)], 1u);
;         const unsigned gen = old / nloc;
;         if (old + 1u == (gen + 1u) * nloc) {
;             __builtin_amdgcn_fence(__ATOMIC_RELEASE, "agent");
;             asm volatile("s_waitcnt vmcnt(0)" ::: "memory");
;             const unsigned og = xb_add(&bar[XB_TOP], 1u);
;             const unsigned tg = og / nx;
;             if (og + 1u == (tg + 1u) * nx) xb_add(&bar[XB_TOPGEN], 1u);
;             else XB_SPIN(xb_ld(&bar[XB_TOPGEN]) == tg, bar);
;             __builtin_amdgcn_fence(__ATOMIC_ACQUIRE, "agent");
;             xb_add(&bar[XB_XGEN(b.x)], 1u);
;             asm volatile("s_waitcnt vmcnt(0)" ::: "memory");
;         } else {
;             XB_SPIN(xb_ld(&bar[XB_XGEN(b.x)]) == gen, bar);
;             __builtin_amdgcn_fence(__ATOMIC_ACQUIRE, "agent");
;             asm volatile("s_waitcnt vmcnt(0)" ::: "memory");
;         }
.LBB0_134:
	v_readlane_b32 s4, v254, 9
	s_lshl_b32 s4, s4, 8
	v_readlane_b32 s6, v254, 7
	v_readlane_b32 s7, v254, 8
	s_add_u32 s4, s6, s4
	s_addc_u32 s5, s7, 0
	v_mov_b32_e32 v2, 0x1000
	v_mov_b32_e32 v4, 1
	global_atomic_add v4, v2, v4, s[4:5] offset:1024 sc0
	v_cvt_f32_u32_e32 v2, v3
	v_sub_u32_e32 v5, 0, v3
	v_rcp_iflag_f32_e32 v2, v2
	s_nop 0
	v_mul_f32_e32 v2, 0x4f7ffffe, v2
	v_cvt_u32_f32_e32 v2, v2
	v_mul_lo_u32 v5, v5, v2
	v_mul_hi_u32 v5, v2, v5
	v_add_u32_e32 v2, v2, v5
	s_waitcnt vmcnt(0)
	v_mul_hi_u32 v2, v4, v2
	v_mul_lo_u32 v5, v2, v3
	v_sub_u32_e32 v5, v4, v5
	v_add_u32_e32 v6, 1, v2
	v_cmp_ge_u32_e32 vcc, v5, v3
	v_add_u32_e32 v4, 1, v4
	s_nop 0
	v_cndmask_b32_e32 v2, v2, v6, vcc
	v_sub_u32_e32 v6, v5, v3
	v_cndmask_b32_e32 v5, v5, v6, vcc
	v_add_u32_e32 v6, 1, v2
	v_cmp_ge_u32_e32 vcc, v5, v3
	s_nop 1
	v_cndmask_b32_e32 v2, v2, v6, vcc
	v_mul_lo_u32 v5, v3, v2
	v_add_u32_e32 v3, v5, v3
	v_cmp_ne_u32_e32 vcc, v4, v3
	s_and_saveexec_b64 s[6:7], vcc
	s_xor_b64 s[6:7], exec, s[6:7]
	s_cbranch_execz .LBB0_148
	s_waitcnt lgkmcnt(0)
	v_readlane_b32 s10, v254, 7
	v_readlane_b32 s11, v254, 8
	v_mov_b32_e32 v1, 0
	s_add_u32 s10, s10, 0x3500
	s_addc_u32 s11, s11, 0
	s_mov_b64 s[8:9], exec
	s_mov_b32 s22, 0
	global_load_dword v10, v1, s[10:11] sc1
.Lbns_1:
	s_sleep 7
	global_load_dword v11, v1, s[10:11] sc1
	s_waitcnt vmcnt(1)
	v_cmp_ne_u32_e32 vcc, v10, v2
	s_cbranch_vccnz .Lbnd_1
	s_sleep 7
	global_load_dword v10, v1, s[10:11] sc1
	s_waitcnt vmcnt(1)
	v_cmp_ne_u32_e32 vcc, v11, v2
	s_cbranch_vccnz .Lbnd_1
	s_add_i32 s22, s22, 1
	s_cmp_lt_u32 s22, 0x80000
	s_cbranch_scc1 .Lbns_1
.Lbnd_1:
.LBB0_147:
	s_or_b64 exec, exec, s[8:9]
	s_waitcnt vmcnt(0)
	buffer_inv sc1
	s_waitcnt vmcnt(0)

; __device__ __forceinline__ unsigned xb_ld(unsigned* p)              { return __hip_atomic_load(p, __ATOMIC_RELAXED, __HIP_MEMORY_SCOPE_AGENT); }
; __device__ __forceinline__ unsigned xb_add(unsigned* p, unsigned v) { return __hip_atomic_fetch_add(p, v, __ATOMIC_RELAXED, __HIP_MEMORY_SCOPE_AGENT); }
; #define XB_SPIN(cond, bar) do { unsigned _sp = 0; while (cond) { __builtin_amdgcn_s_sleep(1); \
;     if ((++_sp & 255u) == 0u) { if (xb_ld(&(bar)[XB_TMO])) break; if (_sp > XB_SPIN_CAP) { atomicAdd(&(bar)[XB_TMO], 1u); break; } } } } while (0)
; __device__ __forceinline__ void xcd_barrier(const XcdBarrier& b) {
;     ...
;             __builtin_amdgcn_fence(__ATOMIC_RELEASE, "agent");
;             asm volatile("s_waitcnt vmcnt(0)" ::: "memory");
;             const unsigned og = xb_add(&bar[XB_TOP], 1u);
;             const unsigned tg = og / nx;
;             if (og + 1u == (tg + 1u) * nx) xb_add(&bar[XB_TOPGEN], 1u);
;             else XB_SPIN(xb_ld(&bar[XB_TOPGEN]) == tg, bar);
.LBB0_151:
	s_or_b64 exec, exec, s[8:9]
	v_cvt_f32_u32_e32 v4, v1
	s_waitcnt vmcnt(0)
	v_readfirstlane_b32 s6, v3
	s_mov_b64 s[10:11], -1
	v_rcp_iflag_f32_e32 v4, v4
	v_add_u32_e32 v2, s6, v2
	v_add_u32_e32 v5, 1, v2
	v_readlane_b32 s6, v254, 7
	v_mul_f32_e32 v3, 0x4f7ffffe, v4
	v_cvt_u32_f32_e32 v3, v3
	v_sub_u32_e32 v4, 0, v1
	v_readlane_b32 s7, v254, 8
	s_add_u32 s8, s6, 0x3500
	v_mul_lo_u32 v4, v4, v3
	v_mul_hi_u32 v4, v3, v4
	v_add_u32_e32 v3, v3, v4
	v_mul_hi_u32 v3, v2, v3
	v_mul_lo_u32 v4, v3, v1
	v_sub_u32_e32 v2, v2, v4
	v_add_u32_e32 v6, 1, v3
	v_cmp_ge_u32_e32 vcc, v2, v1
	v_sub_u32_e32 v4, v2, v1
	s_addc_u32 s9, s7, 0
	v_cndmask_b32_e32 v3, v3, v6, vcc
	v_cndmask_b32_e32 v2, v2, v4, vcc
	v_add_u32_e32 v4, 1, v3
	v_cmp_ge_u32_e32 vcc, v2, v1
	s_nop 1
	v_cndmask_b32_e32 v4, v3, v4, vcc
	v_mul_lo_u32 v2, v1, v4
	v_add_u32_e32 v1, v2, v1
	v_cmp_ne_u32_e32 vcc, v5, v1
	v_mov_b64_e32 v[2:3], s[8:9]
	s_and_saveexec_b64 s[6:7], vcc
	s_cbranch_execz .LBB0_163
	v_mov_b32_e32 v1, 0
	s_mov_b64 s[16:17], 0
	s_mov_b64 s[14:15], exec
	v_readlane_b32 s10, v254, 7
	v_readlane_b32 s11, v254, 8
	s_add_u32 s10, s10, 0x200
	s_addc_u32 s11, s11, 0
	s_mov_b32 s24, 0
	global_load_dword v10, v1, s[8:9] sc1
.Lbls_1:
	s_sleep 7
	global_load_dword v11, v1, s[8:9] sc1
	s_waitcnt vmcnt(1)
	v_cmp_ne_u32_e32 vcc, v10, v4
	s_cbranch_vccnz .Lbld_1
	s_sleep 7
	global_load_dword v10, v1, s[8:9] sc1
	s_waitcnt vmcnt(1)
	v_cmp_ne_u32_e32 vcc, v11, v4
	s_cbranch_vccnz .Lbld_1
	s_add_i32 s24, s24, 1
	s_cmp_lt_u32 s24, 0x80000
	s_cbranch_scc1 .Lbls_1
.Lbld_1:
.LBB0_162:
	s_or_b64 exec, exec, s[14:15]
	v_mov_b64_e32 v[2:3], s[10:11]
	s_orn2_b64 s[10:11], s[16:17], exec

; __device__ __forceinline__ unsigned xb_ld(unsigned* p)              { return __hip_atomic_load(p, __ATOMIC_RELAXED, __HIP_MEMORY_SCOPE_AGENT); }
; __device__ __forceinline__ unsigned xb_add(unsigned* p, unsigned v) { return __hip_atomic_fetch_add(p, v, __ATOMIC_RELAXED, __HIP_MEMORY_SCOPE_AGENT); }
; #define XB_SPIN(cond, bar) do { unsigned _sp = 0; while (cond) { __builtin_amdgcn_s_sleep(1); \
;     if ((++_sp & 255u) == 0u) { if (xb_ld(&(bar)[XB_TMO])) break; if (_sp > XB_SPIN_CAP) { atomicAdd(&(bar)[XB_TMO], 1u); break; } } } } while (0)
; __device__ __forceinline__ void xcd_barrier(const XcdBarrier& b) {
;     ...
;             __builtin_amdgcn_fence(__ATOMIC_RELEASE, "agent");
;             asm volatile("s_waitcnt vmcnt(0)" ::: "memory");
;             const unsigned og = xb_add(&bar[XB_TOP], 1u);
;             const unsigned tg = og / nx;
;             if (og + 1u == (tg + 1u) * nx) xb_add(&bar[XB_TOPGEN], 1u);
;             else XB_SPIN(xb_ld(&bar[XB_TOPGEN]) == tg, bar);
.LBB0_641:
	s_or_b64 exec, exec, s[8:9]
	v_cvt_f32_u32_e32 v4, v1
	s_waitcnt vmcnt(0)
	v_readfirstlane_b32 s6, v3
	s_mov_b64 s[10:11], -1
	v_rcp_iflag_f32_e32 v4, v4
	v_add_u32_e32 v2, s6, v2
	v_add_u32_e32 v5, 1, v2
	v_readlane_b32 s6, v254, 7
	v_mul_f32_e32 v3, 0x4f7ffffe, v4
	v_cvt_u32_f32_e32 v3, v3
	v_sub_u32_e32 v4, 0, v1
	v_readlane_b32 s7, v254, 8
	s_add_u32 s8, s6, 0x3500
	v_mul_lo_u32 v4, v4, v3
	v_mul_hi_u32 v4, v3, v4
	v_add_u32_e32 v3, v3, v4
	v_mul_hi_u32 v3, v2, v3
	v_mul_lo_u32 v4, v3, v1
	v_sub_u32_e32 v2, v2, v4
	v_add_u32_e32 v6, 1, v3
	v_cmp_ge_u32_e32 vcc, v2, v1
	v_sub_u32_e32 v4, v2, v1
	s_addc_u32 s9, s7, 0
	v_cndmask_b32_e32 v3, v3, v6, vcc
	v_cndmask_b32_e32 v2, v2, v4, vcc
	v_add_u32_e32 v4, 1, v3
	v_cmp_ge_u32_e32 vcc, v2, v1
	s_nop 1
	v_cndmask_b32_e32 v4, v3, v4, vcc
	v_mul_lo_u32 v2, v1, v4
	v_add_u32_e32 v1, v2, v1
	v_cmp_ne_u32_e32 vcc, v5, v1
	v_mov_b64_e32 v[2:3], s[8:9]
	s_and_saveexec_b64 s[6:7], vcc
	s_cbranch_execz .LBB0_653
	v_mov_b32_e32 v1, 0
	s_mov_b64 s[14:15], 0
	s_mov_b64 s[12:13], exec
	v_readlane_b32 s10, v254, 7
	v_readlane_b32 s11, v254, 8
	s_add_u32 s10, s10, 0x200
	s_addc_u32 s11, s11, 0
	s_mov_b32 s24, 0
	global_load_dword v10, v1, s[8:9] sc1

; __device__ __forceinline__ unsigned xb_ld(unsigned* p)              { return __hip_atomic_load(p, __ATOMIC_RELAXED, __HIP_MEMORY_SCOPE_AGENT); }
; #define XB_SPIN(cond, bar) do { unsigned _sp = 0; while (cond) { __builtin_amdgcn_s_sleep(1); \
;     if ((++_sp & 255u) == 0u) { if (xb_ld(&(bar)[XB_TMO])) break; if (_sp > XB_SPIN_CAP) { atomicAdd(&(bar)[XB_TMO], 1u); break; } } } } while (0)
; __device__ __forceinline__ void xcd_barrier(const XcdBarrier& b) {
;     ...
;             else XB_SPIN(xb_ld(&bar[XB_TOPGEN]) == tg, bar);
.Lbld_3:
.LBB0_652:
	s_or_b64 exec, exec, s[12:13]
	v_mov_b64_e32 v[2:3], s[10:11]
	s_orn2_b64 s[10:11], s[14:15], exec

; __device__ __forceinline__ unsigned xb_ld(unsigned* p)              { return __hip_atomic_load(p, __ATOMIC_RELAXED, __HIP_MEMORY_SCOPE_AGENT); }
; __device__ __forceinline__ unsigned xb_add(unsigned* p, unsigned v) { return __hip_atomic_fetch_add(p, v, __ATOMIC_RELAXED, __HIP_MEMORY_SCOPE_AGENT); }
; #define XB_SPIN(cond, bar) do { unsigned _sp = 0; while (cond) { __builtin_amdgcn_s_sleep(1); \
;     if ((++_sp & 255u) == 0u) { if (xb_ld(&(bar)[XB_TMO])) break; if (_sp > XB_SPIN_CAP) { atomicAdd(&(bar)[XB_TMO], 1u); break; } } } } while (0)
; __device__ __forceinline__ void xcd_barrier(const XcdBarrier& b) {
;     ...
;         const unsigned old = xb_add(&bar[XB_XSUB(b.x)], 1u);
;         const unsigned gen = old / nloc;
;         if (old + 1u == (gen + 1u) * nloc) {
;             __builtin_amdgcn_fence(__ATOMIC_RELEASE, "agent");
;             asm volatile("s_waitcnt vmcnt(0)" ::: "memory");
;             const unsigned og = xb_add(&bar[XB_TOP], 1u);
;             const unsigned tg = og / nx;
;             if (og + 1u == (tg + 1u) * nx) xb_add(&bar[XB_TOPGEN], 1u);
;             else XB_SPIN(xb_ld(&bar[XB_TOPGEN]) == tg, bar);
;             __builtin_amdgcn_fence(__ATOMIC_ACQUIRE, "agent");
;             xb_add(&bar[XB_XGEN(b.x)], 1u);
;             asm volatile("s_waitcnt vmcnt(0)" ::: "memory");
;         } else {
;             XB_SPIN(xb_ld(&bar[XB_XGEN(b.x)]) == gen, bar);
;             __builtin_amdgcn_fence(__ATOMIC_ACQUIRE, "agent");
;             asm volatile("s_waitcnt vmcnt(0)" ::: "memory");
;         }
.LBB0_3529:
	v_readlane_b32 s4, v254, 9
	s_lshl_b32 s4, s4, 8
	v_readlane_b32 s6, v254, 7
	v_readlane_b32 s7, v254, 8
	s_add_u32 s4, s6, s4
	s_addc_u32 s5, s7, 0
	v_mov_b32_e32 v1, 0x1000
	v_mov_b32_e32 v3, 1
	global_atomic_add v3, v1, v3, s[4:5] offset:1024 sc0
	v_cvt_f32_u32_e32 v1, v2
	v_sub_u32_e32 v4, 0, v2
	v_rcp_iflag_f32_e32 v1, v1
	s_nop 0
	v_mul_f32_e32 v1, 0x4f7ffffe, v1
	v_cvt_u32_f32_e32 v1, v1
	v_mul_lo_u32 v4, v4, v1
	v_mul_hi_u32 v4, v1, v4
	v_add_u32_e32 v1, v1, v4
	s_waitcnt vmcnt(0)
	v_mul_hi_u32 v1, v3, v1
	v_mul_lo_u32 v4, v1, v2
	v_sub_u32_e32 v4, v3, v4
	v_add_u32_e32 v5, 1, v1
	v_cmp_ge_u32_e32 vcc, v4, v2
	v_add_u32_e32 v3, 1, v3
	s_nop 0
	v_cndmask_b32_e32 v1, v1, v5, vcc
	v_sub_u32_e32 v5, v4, v2
	v_cndmask_b32_e32 v4, v4, v5, vcc
	v_add_u32_e32 v5, 1, v1
	v_cmp_ge_u32_e32 vcc, v4, v2
	s_nop 1
	v_cndmask_b32_e32 v1, v1, v5, vcc
	v_mul_lo_u32 v4, v2, v1
	v_add_u32_e32 v2, v4, v2
	v_cmp_ne_u32_e32 vcc, v3, v2
	s_and_saveexec_b64 s[6:7], vcc
	s_xor_b64 s[6:7], exec, s[6:7]
	s_cbranch_execz .LBB0_3543
	s_waitcnt lgkmcnt(0)
	v_readlane_b32 s10, v254, 7
	v_readlane_b32 s11, v254, 8
	v_mov_b32_e32 v0, 0
	s_add_u32 s10, s10, 0x3500
	s_addc_u32 s11, s11, 0
	s_mov_b64 s[8:9], exec
	s_mov_b32 s22, 0
	global_load_dword v10, v0, s[10:11] sc1
.Lbns_22:
	s_sleep 7
	global_load_dword v11, v0, s[10:11] sc1
	s_waitcnt vmcnt(1)
	v_cmp_ne_u32_e32 vcc, v10, v1
	s_cbranch_vccnz .Lbnd_22
	s_sleep 7
	global_load_dword v10, v0, s[10:11] sc1
	s_waitcnt vmcnt(1)
	v_cmp_ne_u32_e32 vcc, v11, v1
	s_cbranch_vccnz .Lbnd_22
	s_add_i32 s22, s22, 1
	s_cmp_lt_u32 s22, 0x80000
	s_cbranch_scc1 .Lbns_22

; __device__ __forceinline__ unsigned xb_ld(unsigned* p)              { return __hip_atomic_load(p, __ATOMIC_RELAXED, __HIP_MEMORY_SCOPE_AGENT); }
; __device__ __forceinline__ unsigned xb_add(unsigned* p, unsigned v) { return __hip_atomic_fetch_add(p, v, __ATOMIC_RELAXED, __HIP_MEMORY_SCOPE_AGENT); }
; #define XB_SPIN(cond, bar) do { unsigned _sp = 0; while (cond) { __builtin_amdgcn_s_sleep(1); \
;     if ((++_sp & 255u) == 0u) { if (xb_ld(&(bar)[XB_TMO])) break; if (_sp > XB_SPIN_CAP) { atomicAdd(&(bar)[XB_TMO], 1u); break; } } } } while (0)
; __device__ __forceinline__ void xcd_barrier(const XcdBarrier& b) {
;     ...
;             __builtin_amdgcn_fence(__ATOMIC_RELEASE, "agent");
;             asm volatile("s_waitcnt vmcnt(0)" ::: "memory");
;             const unsigned og = xb_add(&bar[XB_TOP], 1u);
;             const unsigned tg = og / nx;
;             if (og + 1u == (tg + 1u) * nx) xb_add(&bar[XB_TOPGEN], 1u);
;             else XB_SPIN(xb_ld(&bar[XB_TOPGEN]) == tg, bar);
.LBB0_3546:
	s_or_b64 exec, exec, s[8:9]
	v_cvt_f32_u32_e32 v3, v0
	s_waitcnt vmcnt(0)
	v_readfirstlane_b32 s6, v2
	s_mov_b64 s[10:11], -1
	v_rcp_iflag_f32_e32 v3, v3
	v_add_u32_e32 v1, s6, v1
	v_add_u32_e32 v4, 1, v1
	v_readlane_b32 s6, v254, 7
	v_mul_f32_e32 v2, 0x4f7ffffe, v3
	v_cvt_u32_f32_e32 v2, v2
	v_sub_u32_e32 v3, 0, v0
	v_readlane_b32 s7, v254, 8
	s_add_u32 s8, s6, 0x3500
	v_mul_lo_u32 v3, v3, v2
	v_mul_hi_u32 v3, v2, v3
	v_add_u32_e32 v2, v2, v3
	v_mul_hi_u32 v2, v1, v2
	v_mul_lo_u32 v3, v2, v0
	v_sub_u32_e32 v1, v1, v3
	v_add_u32_e32 v5, 1, v2
	v_cmp_ge_u32_e32 vcc, v1, v0
	v_sub_u32_e32 v3, v1, v0
	s_addc_u32 s9, s7, 0
	v_cndmask_b32_e32 v2, v2, v5, vcc
	v_cndmask_b32_e32 v1, v1, v3, vcc
	v_add_u32_e32 v3, 1, v2
	v_cmp_ge_u32_e32 vcc, v1, v0
	s_nop 1
	v_cndmask_b32_e32 v2, v2, v3, vcc
	v_mul_lo_u32 v1, v0, v2
	v_add_u32_e32 v0, v1, v0
	v_cmp_ne_u32_e32 vcc, v4, v0
	v_mov_b64_e32 v[0:1], s[8:9]
	s_and_saveexec_b64 s[6:7], vcc
	s_cbranch_execz .LBB0_3558
	v_mov_b32_e32 v0, 0
	s_mov_b64 s[14:15], 0
	s_mov_b64 s[12:13], exec
	v_readlane_b32 s10, v254, 7
	v_readlane_b32 s11, v254, 8
	s_add_u32 s10, s10, 0x200
	s_addc_u32 s11, s11, 0
	s_mov_b32 s24, 0
	global_load_dword v10, v0, s[8:9] sc1
.Lbls_22:
	s_sleep 7
	global_load_dword v11, v0, s[8:9] sc1
	s_waitcnt vmcnt(1)
	v_cmp_ne_u32_e32 vcc, v10, v2
	s_cbranch_vccnz .Lbld_22
	s_sleep 7
	global_load_dword v10, v0, s[8:9] sc1
	s_waitcnt vmcnt(1)
	v_cmp_ne_u32_e32 vcc, v11, v2
	s_cbranch_vccnz .Lbld_22
	s_add_i32 s24, s24, 1
	s_cmp_lt_u32 s24, 0x80000
	s_cbranch_scc1 .Lbls_22
.Lbld_22:
.LBB0_3557:
	s_or_b64 exec, exec, s[12:13]
	v_mov_b64_e32 v[0:1], s[10:11]
	s_orn2_b64 s[10:11], s[14:15], exec
